# on top of the persistent -mhat block: row-max chain drops redundant self-max canonicalizations (4 VALU/step) and the row-sum tail folds a +0 add into the l accumulation (1 VALU/step)
# speedup vs baseline: 1.0147x; 1.0068x over previous
.LBB0_1277:
	s_lshl_b32 s18, s23, 1
	v_add_u32_e32 v237, s18, v214
	ds_read_b64_tr_b16 v[192:193], v237 offset:24576
	v_add_f32_e32 v112, v80, v81
	v_add_f32_e32 v112, v82, v112
	v_add_f32_e32 v112, v83, v112
	v_add_f32_e32 v112, v84, v112
	v_add_f32_e32 v128, v85, v112
	s_waitcnt lgkmcnt(8)
	v_mfma_f32_32x32x16_bf16 v[112:127], v[188:191], v[156:159], v[238:253]
	v_cvt_pk_bf16_f32 v148, v80, v81
	v_cvt_pk_bf16_f32 v149, v82, v83
	ds_read_b64_tr_b16 v[194:195], v237 offset:25088
	s_waitcnt lgkmcnt(8)
	v_mfma_f32_32x32x16_bf16 v[96:111], v[184:187], v[156:159], v[238:253]
	v_add_f32_e32 v80, v86, v128
	v_add_f32_e32 v80, v87, v80
	v_add_f32_e32 v80, v88, v80
	v_add_f32_e32 v82, v89, v80
	v_cvt_pk_bf16_f32 v150, v84, v85
	v_cvt_pk_bf16_f32 v151, v86, v87
	ds_read_b64_tr_b16 v[80:81], v237 offset:28672
	s_waitcnt lgkmcnt(8)
	v_mfma_f32_32x32x16_bf16 v[112:127], v[180:183], v[152:155], v[112:127]
	v_add_f32_e32 v82, v90, v82
	v_add_f32_e32 v82, v91, v82
	v_add_f32_e32 v82, v92, v82
	v_add_f32_e32 v84, v93, v82
	v_cvt_pk_bf16_f32 v140, v88, v89
	v_cvt_pk_bf16_f32 v141, v90, v91
	ds_read_b64_tr_b16 v[82:83], v237 offset:29184
	s_waitcnt lgkmcnt(8)
	v_mfma_f32_32x32x16_bf16 v[96:111], v[176:179], v[152:155], v[96:111]
	v_add_f32_e32 v84, v94, v84
	v_add_f32_e32 v84, v95, v84
	v_add_f32_e32 v84, v64, v84
	v_add_f32_e32 v86, v65, v84
	v_cvt_pk_bf16_f32 v142, v92, v93
	v_cvt_pk_bf16_f32 v143, v94, v95
	ds_read_b64_tr_b16 v[84:85], v237 offset:32768
	s_waitcnt lgkmcnt(8)
	v_mfma_f32_32x32x16_bf16 v[112:127], v[172:175], v[144:147], v[112:127]
	v_add_f32_e32 v86, v66, v86
	v_add_f32_e32 v86, v67, v86
	v_add_f32_e32 v86, v68, v86
	v_add_f32_e32 v88, v69, v86
	v_cvt_pk_bf16_f32 v132, v64, v65
	v_cvt_pk_bf16_f32 v133, v66, v67
	ds_read_b64_tr_b16 v[86:87], v237 offset:33280
	s_waitcnt lgkmcnt(8)
	v_mfma_f32_32x32x16_bf16 v[96:111], v[168:171], v[144:147], v[96:111]
	v_add_f32_e32 v64, v70, v88
	v_add_f32_e32 v64, v71, v64
	v_add_f32_e32 v64, v72, v64
	v_add_f32_e32 v66, v73, v64
	v_cvt_pk_bf16_f32 v134, v68, v69
	v_cvt_pk_bf16_f32 v135, v70, v71
	ds_read_b64_tr_b16 v[64:65], v237 offset:36864
	s_waitcnt lgkmcnt(8)
	v_mfma_f32_32x32x16_bf16 v[112:127], v[164:167], v[136:139], v[112:127]
	v_add_f32_e32 v66, v74, v66
	v_add_f32_e32 v66, v75, v66
	v_add_f32_e32 v66, v76, v66
	v_add_f32_e32 v68, v77, v66
	v_cvt_pk_bf16_f32 v128, v72, v73
	v_cvt_pk_bf16_f32 v129, v74, v75
	ds_read_b64_tr_b16 v[66:67], v237 offset:37376
	s_waitcnt lgkmcnt(8)
	v_mfma_f32_32x32x16_bf16 v[96:111], v[160:163], v[136:139], v[96:111]
	v_add_f32_e32 v68, v78, v68
	v_add_f32_e32 v68, v79, v68
	v_add_f32_e32 v236, v236, v68
	v_cvt_pk_bf16_f32 v130, v76, v77
	v_cvt_pk_bf16_f32 v131, v78, v79
	s_movk_i32 s30, 0xc000
	v_lshl_add_u64 v[68:69], v[206:207], 0, s[44:45]
	s_add_i32 s18, s86, s89
	s_mov_b32 s31, -1
	s_mov_b32 s23, m0
	s_mov_b32 m0, s18
	s_nop 0
	global_load_lds_dwordx4 v[68:69], off
	s_mov_b32 m0, s23
	v_lshl_add_u64 v[68:69], v[204:205], 0, s[30:31]
	s_lshl_b32 s18, s37, 1
	s_add_i32 s18, s18, s90
	s_mov_b32 s23, m0
	s_mov_b32 m0, s18
	s_nop 0
	global_load_lds_dwordx4 v[68:69], off
	s_mov_b32 m0, s23
	v_lshl_add_u64 v[68:69], v[204:205], 0, s[44:45]
	s_addk_i32 s18, 0x2000
	s_mov_b32 s23, m0
	s_mov_b32 m0, s18
	s_nop 0
	global_load_lds_dwordx4 v[68:69], off
	s_mov_b32 m0, s23
	v_max_f32_e32 v68, v113, v112
	v_max3_f32 v69, v114, v115, v97
	v_max3_f32 v68, v68, v96, v98
	v_max3_f32 v68, v68, v99, v116
	v_max3_f32 v69, v69, v118, v119
	v_max3_f32 v68, v68, v117, v100
	v_max3_f32 v69, v69, v102, v103
	v_max3_f32 v68, v68, v101, v120
	v_max3_f32 v69, v69, v122, v123
	v_max3_f32 v68, v68, v121, v104
	v_max3_f32 v69, v69, v106, v107
	v_max3_f32 v68, v68, v105, v124
	v_max3_f32 v69, v69, v126, v127
	v_max3_f32 v68, v68, v125, v108
	v_max3_f32 v69, v69, v110, v111
	v_max3_f32 v68, v68, v109, v69
	v_mov_b32_e32 v69, v68
	s_nop 1
	v_permlane32_swap_b32_e32 v68, v69
	v_max_f32_e32 v68, v69, v68
	v_cmp_lt_f32_e32 vcc, s71, v68
	s_cmp_lg_u64 vcc, 0
	s_cselect_b64 s[50:51], -1, 0
	s_cbranch_vccnz .LBB0_1285

.LBB0_1280:
	s_add_i32 s18, s37, 0x2000
	s_lshl_b32 s23, s86, 1
	v_add_u32_e32 v237, s23, v214
	ds_read_b64_tr_b16 v[180:181], v237 offset:24576
	s_cmpk_lg_i32 s37, 0x4000
	s_cselect_b32 s86, s18, 0
	v_add_f32_e32 v80, v112, v113
	v_add_f32_e32 v80, v114, v80
	v_add_f32_e32 v80, v115, v80
	v_add_f32_e32 v80, v116, v80
	v_add_f32_e32 v128, v117, v80
	s_waitcnt lgkmcnt(8)
	v_mfma_f32_32x32x16_bf16 v[80:95], v[192:195], v[156:159], v[238:253]
	v_cvt_pk_bf16_f32 v148, v112, v113
	v_cvt_pk_bf16_f32 v149, v114, v115
	ds_read_b64_tr_b16 v[182:183], v237 offset:25088
	s_waitcnt lgkmcnt(8)
	v_mfma_f32_32x32x16_bf16 v[64:79], v[188:191], v[156:159], v[238:253]
	v_add_f32_e32 v112, v118, v128
	v_add_f32_e32 v112, v119, v112
	v_add_f32_e32 v112, v120, v112
	v_add_f32_e32 v114, v121, v112
	v_cvt_pk_bf16_f32 v150, v116, v117
	v_cvt_pk_bf16_f32 v151, v118, v119
	ds_read_b64_tr_b16 v[112:113], v237 offset:28672
	s_waitcnt lgkmcnt(8)
	v_mfma_f32_32x32x16_bf16 v[80:95], v[184:187], v[152:155], v[80:95]
	v_add_f32_e32 v114, v122, v114
	v_add_f32_e32 v114, v123, v114
	v_add_f32_e32 v114, v124, v114
	v_add_f32_e32 v116, v125, v114
	v_cvt_pk_bf16_f32 v140, v120, v121
	v_cvt_pk_bf16_f32 v141, v122, v123
	ds_read_b64_tr_b16 v[114:115], v237 offset:29184
	s_waitcnt lgkmcnt(8)
	v_mfma_f32_32x32x16_bf16 v[64:79], v[176:179], v[152:155], v[64:79]
	v_add_f32_e32 v116, v126, v116
	v_add_f32_e32 v116, v127, v116
	v_add_f32_e32 v116, v96, v116
	v_add_f32_e32 v118, v97, v116
	v_cvt_pk_bf16_f32 v142, v124, v125
	v_cvt_pk_bf16_f32 v143, v126, v127
	ds_read_b64_tr_b16 v[116:117], v237 offset:32768
	s_waitcnt lgkmcnt(8)
	v_mfma_f32_32x32x16_bf16 v[80:95], v[172:175], v[144:147], v[80:95]
	v_add_f32_e32 v118, v98, v118
	v_add_f32_e32 v118, v99, v118
	v_add_f32_e32 v118, v100, v118
	v_add_f32_e32 v120, v101, v118
	v_cvt_pk_bf16_f32 v132, v96, v97
	v_cvt_pk_bf16_f32 v133, v98, v99
	ds_read_b64_tr_b16 v[118:119], v237 offset:33280
	s_waitcnt lgkmcnt(8)
	v_mfma_f32_32x32x16_bf16 v[64:79], v[168:171], v[144:147], v[64:79]
	v_add_f32_e32 v96, v102, v120
	v_add_f32_e32 v96, v103, v96
	v_add_f32_e32 v96, v104, v96
	v_add_f32_e32 v98, v105, v96
	v_cvt_pk_bf16_f32 v134, v100, v101
	v_cvt_pk_bf16_f32 v135, v102, v103
	ds_read_b64_tr_b16 v[96:97], v237 offset:36864
	s_waitcnt lgkmcnt(8)
	v_mfma_f32_32x32x16_bf16 v[80:95], v[164:167], v[136:139], v[80:95]
	v_add_f32_e32 v98, v106, v98
	v_add_f32_e32 v98, v107, v98
	v_add_f32_e32 v98, v108, v98
	v_add_f32_e32 v100, v109, v98
	v_cvt_pk_bf16_f32 v128, v104, v105
	v_cvt_pk_bf16_f32 v129, v106, v107
	ds_read_b64_tr_b16 v[98:99], v237 offset:37376
	s_waitcnt lgkmcnt(8)
	v_mfma_f32_32x32x16_bf16 v[64:79], v[160:163], v[136:139], v[64:79]
	v_add_f32_e32 v100, v110, v100
	v_add_f32_e32 v100, v111, v100
	v_add_f32_e32 v236, v236, v100
	v_cvt_pk_bf16_f32 v130, v108, v109
	v_cvt_pk_bf16_f32 v131, v110, v111
	s_add_i32 s18, s37, s89
	s_mov_b32 s23, m0
	s_mov_b32 m0, s18
	s_nop 0
	global_load_lds_dwordx4 v[206:207], off
	s_mov_b32 m0, s23
	s_lshl_b32 s18, s86, 1
	s_add_i32 s18, s18, s90
	s_mov_b32 s23, m0
	s_mov_b32 m0, s18
	s_nop 0
	global_load_lds_dwordx4 v[204:205], off
	s_mov_b32 m0, s23
	v_lshl_add_u64 v[100:101], v[204:205], 0, s[14:15]
	s_addk_i32 s18, 0x2000
	s_mov_b32 s23, m0
	s_mov_b32 m0, s18
	s_nop 0
	global_load_lds_dwordx4 v[100:101], off
	s_mov_b32 m0, s23
	v_max_f32_e32 v100, v81, v80
	v_max3_f32 v101, v82, v83, v65
	v_max3_f32 v100, v100, v64, v66
	v_max3_f32 v100, v100, v67, v84
	v_max3_f32 v101, v101, v86, v87
	v_max3_f32 v100, v100, v85, v68
	v_max3_f32 v101, v101, v70, v71
	v_max3_f32 v100, v100, v69, v88
	v_max3_f32 v101, v101, v90, v91
	v_max3_f32 v100, v100, v89, v72
	v_max3_f32 v101, v101, v74, v75
	v_max3_f32 v100, v100, v73, v92
	v_max3_f32 v101, v101, v94, v95
	v_max3_f32 v100, v100, v93, v76
	v_max3_f32 v101, v101, v78, v79
	v_max3_f32 v100, v100, v77, v101
	v_mov_b32_e32 v101, v100
	s_nop 1
	v_permlane32_swap_b32_e32 v100, v101
	v_max_f32_e32 v100, v101, v100
	v_cmp_lt_f32_e32 vcc, s71, v100
	s_cmp_lg_u64 vcc, 0
	s_cselect_b64 s[50:51], -1, 0
	s_cbranch_vccnz .LBB0_1288
